# P5 (W_out + residual) epilogue rewritten by hand like P7: permuted accumulators, coalesced XN loads / X1B stores, DPP row sums
# baseline (speedup 1.0000x reference)
.LBB0_866:
	v_readlane_b32 s76, v244, 0
	v_readlane_b32 s77, v244, 1
	v_readlane_b32 s78, v244, 2
	v_readlane_b32 s79, v244, 3
	v_readlane_b32 s80, v244, 4
	v_readlane_b32 s81, v244, 5
	v_readlane_b32 s82, v244, 6
	v_readlane_b32 s83, v244, 7
	v_readlane_b32 s84, v244, 8
	v_readlane_b32 s85, v244, 9
	v_readlane_b32 s86, v244, 10
	v_readlane_b32 s87, v244, 11
	v_readlane_b32 s88, v244, 12
	v_readlane_b32 s89, v244, 13
	v_readlane_b32 s90, v244, 14
	v_readlane_b32 s91, v244, 15
	v_and_b32_e32 v198, 3, v215
	v_bfe_u32 v199, v215, 4, 2
	v_and_or_b32 v199, v215, 12, v199
	v_lshl_or_b32 v196, v198, 4, v199
	v_lshlrev_b32_e32 v196, 2, v196
	v_and_or_b32 v199, v197, -16, v199
	v_and_b32_e32 v200, 0x60, v211
	v_lshl_or_b32 v200, v198, 3, v200
	v_lshl_add_u32 v199, s72, 8, v199
	v_lshl_or_b32 v200, s73, 8, v200
	v_lshlrev_b32_e32 v176, 2, v199
	v_lshlrev_b32_e32 v199, 11, v199
	v_lshl_add_u32 v168, v200, 1, v199
	v_add_u32_e32 v169, 0x8000, v168
	v_add_u32_e32 v170, 0x10000, v168
	v_add_u32_e32 v171, 0x18000, v168
	v_add_u32_e32 v172, 0x40000, v168
	v_add_u32_e32 v173, 0x48000, v168
	v_add_u32_e32 v174, 0x50000, v168
	v_add_u32_e32 v175, 0x58000, v168
	s_mov_b32 s10, 0x11111111
	s_mov_b32 s11, s10
	v_lshlrev_b32_e32 v200, 2, v200
	global_load_dwordx4 v[228:231], v200, s[80:81]
	global_load_dwordx4 v[232:235], v200, s[80:81] offset:16
	global_load_dwordx4 v[180:183], v200, s[80:81] offset:512
	global_load_dwordx4 v[184:187], v200, s[80:81] offset:528
	global_load_dword v190, v176, s[12:13]
	global_load_dwordx4 v[128:131], v168, s[60:61]
	global_load_dwordx4 v[132:135], v168, s[60:61] offset:256
	global_load_dword v192, v176, s[12:13] offset:64
	global_load_dwordx4 v[136:139], v169, s[60:61]
	global_load_dwordx4 v[140:143], v169, s[60:61] offset:256
	global_load_dword v194, v176, s[12:13] offset:128
	global_load_dwordx4 v[144:147], v170, s[60:61]
	global_load_dwordx4 v[148:151], v170, s[60:61] offset:256
	global_load_dword v238, v176, s[12:13] offset:192
	global_load_dwordx4 v[204:207], v171, s[60:61]
	global_load_dwordx4 v[216:219], v171, s[60:61] offset:256
	ds_bpermute_b32 v124, v196, v124
	ds_bpermute_b32 v125, v196, v125
	ds_bpermute_b32 v126, v196, v126
	ds_bpermute_b32 v127, v196, v127
	ds_bpermute_b32 v120, v196, v120
	ds_bpermute_b32 v121, v196, v121
	ds_bpermute_b32 v122, v196, v122
	ds_bpermute_b32 v123, v196, v123
	ds_bpermute_b32 v108, v196, v108
	ds_bpermute_b32 v109, v196, v109
	ds_bpermute_b32 v110, v196, v110
	ds_bpermute_b32 v111, v196, v111
	ds_bpermute_b32 v104, v196, v104
	ds_bpermute_b32 v105, v196, v105
	ds_bpermute_b32 v106, v196, v106
	ds_bpermute_b32 v107, v196, v107
	ds_bpermute_b32 v92, v196, v92
	ds_bpermute_b32 v93, v196, v93
	ds_bpermute_b32 v94, v196, v94
	ds_bpermute_b32 v95, v196, v95
	ds_bpermute_b32 v88, v196, v88
	ds_bpermute_b32 v89, v196, v89
	ds_bpermute_b32 v90, v196, v90
	ds_bpermute_b32 v91, v196, v91
	ds_bpermute_b32 v76, v196, v76
	ds_bpermute_b32 v77, v196, v77
	ds_bpermute_b32 v78, v196, v78
	ds_bpermute_b32 v79, v196, v79
	ds_bpermute_b32 v72, v196, v72
	ds_bpermute_b32 v73, v196, v73
	ds_bpermute_b32 v74, v196, v74
	ds_bpermute_b32 v75, v196, v75
	s_and_b64 vcc, exec, s[40:41]
	s_cbranch_vccz .Lp5_nb
	s_barrier
.Lp5_nb:
	ds_bpermute_b32 v116, v196, v116
	ds_bpermute_b32 v117, v196, v117
	ds_bpermute_b32 v118, v196, v118
	ds_bpermute_b32 v119, v196, v119
	ds_bpermute_b32 v112, v196, v112
	ds_bpermute_b32 v113, v196, v113
	ds_bpermute_b32 v114, v196, v114
	ds_bpermute_b32 v115, v196, v115
	ds_bpermute_b32 v100, v196, v100
	ds_bpermute_b32 v101, v196, v101
	ds_bpermute_b32 v102, v196, v102
	ds_bpermute_b32 v103, v196, v103
	ds_bpermute_b32 v96, v196, v96
	ds_bpermute_b32 v97, v196, v97
	ds_bpermute_b32 v98, v196, v98
	ds_bpermute_b32 v99, v196, v99
	ds_bpermute_b32 v84, v196, v84
	ds_bpermute_b32 v85, v196, v85
	ds_bpermute_b32 v86, v196, v86
	ds_bpermute_b32 v87, v196, v87
	ds_bpermute_b32 v80, v196, v80
	ds_bpermute_b32 v81, v196, v81
	ds_bpermute_b32 v82, v196, v82
	ds_bpermute_b32 v83, v196, v83
	ds_bpermute_b32 v68, v196, v68
	ds_bpermute_b32 v69, v196, v69
	ds_bpermute_b32 v70, v196, v70
	ds_bpermute_b32 v71, v196, v71
	ds_bpermute_b32 v64, v196, v64
	ds_bpermute_b32 v65, v196, v65
	ds_bpermute_b32 v66, v196, v66
	ds_bpermute_b32 v67, v196, v67
	ds_bpermute_b32 v60, v196, v60
	ds_bpermute_b32 v61, v196, v61
	ds_bpermute_b32 v62, v196, v62
	ds_bpermute_b32 v63, v196, v63
	ds_bpermute_b32 v56, v196, v56
	ds_bpermute_b32 v57, v196, v57
	ds_bpermute_b32 v58, v196, v58
	ds_bpermute_b32 v59, v196, v59
	ds_bpermute_b32 v44, v196, v44
	ds_bpermute_b32 v45, v196, v45
	ds_bpermute_b32 v46, v196, v46
	ds_bpermute_b32 v47, v196, v47
	ds_bpermute_b32 v40, v196, v40
	ds_bpermute_b32 v41, v196, v41
	ds_bpermute_b32 v42, v196, v42
	ds_bpermute_b32 v43, v196, v43
	ds_bpermute_b32 v28, v196, v28
	ds_bpermute_b32 v29, v196, v29
	ds_bpermute_b32 v30, v196, v30
	ds_bpermute_b32 v31, v196, v31
	ds_bpermute_b32 v24, v196, v24
	ds_bpermute_b32 v25, v196, v25
	ds_bpermute_b32 v26, v196, v26
	ds_bpermute_b32 v27, v196, v27
	ds_bpermute_b32 v12, v196, v12
	ds_bpermute_b32 v13, v196, v13
	ds_bpermute_b32 v14, v196, v14
	ds_bpermute_b32 v15, v196, v15
	ds_bpermute_b32 v8, v196, v8
	ds_bpermute_b32 v9, v196, v9
	ds_bpermute_b32 v10, v196, v10
	ds_bpermute_b32 v11, v196, v11
	ds_bpermute_b32 v52, v196, v52
	ds_bpermute_b32 v53, v196, v53
	ds_bpermute_b32 v54, v196, v54
	ds_bpermute_b32 v55, v196, v55
	ds_bpermute_b32 v48, v196, v48
	ds_bpermute_b32 v49, v196, v49
	ds_bpermute_b32 v50, v196, v50
	ds_bpermute_b32 v51, v196, v51
	ds_bpermute_b32 v36, v196, v36
	ds_bpermute_b32 v37, v196, v37
	ds_bpermute_b32 v38, v196, v38
	ds_bpermute_b32 v39, v196, v39
	ds_bpermute_b32 v32, v196, v32
	ds_bpermute_b32 v33, v196, v33
	ds_bpermute_b32 v34, v196, v34
	ds_bpermute_b32 v35, v196, v35
	ds_bpermute_b32 v20, v196, v20
	ds_bpermute_b32 v21, v196, v21
	ds_bpermute_b32 v22, v196, v22
	ds_bpermute_b32 v23, v196, v23
	ds_bpermute_b32 v16, v196, v16
	ds_bpermute_b32 v17, v196, v17
	ds_bpermute_b32 v18, v196, v18
	ds_bpermute_b32 v19, v196, v19
	ds_bpermute_b32 v4, v196, v4
	ds_bpermute_b32 v5, v196, v5
	ds_bpermute_b32 v6, v196, v6
	ds_bpermute_b32 v7, v196, v7
	ds_bpermute_b32 v0, v196, v0
	ds_bpermute_b32 v1, v196, v1
	ds_bpermute_b32 v2, v196, v2
	ds_bpermute_b32 v3, v196, v3
	s_waitcnt vmcnt(12)
	v_rcp_f32_e32 v228, v228
	v_rcp_f32_e32 v229, v229
	v_rcp_f32_e32 v230, v230
	v_rcp_f32_e32 v231, v231
	v_rcp_f32_e32 v232, v232
	v_rcp_f32_e32 v233, v233
	v_rcp_f32_e32 v234, v234
	v_rcp_f32_e32 v235, v235
	v_rcp_f32_e32 v180, v180
	v_rcp_f32_e32 v181, v181
	v_rcp_f32_e32 v182, v182
	v_rcp_f32_e32 v183, v183
	v_rcp_f32_e32 v184, v184
	v_rcp_f32_e32 v185, v185
	v_rcp_f32_e32 v186, v186
	v_rcp_f32_e32 v187, v187
	s_waitcnt lgkmcnt(0)
	s_waitcnt vmcnt(9)
	v_lshlrev_b32_e32 v220, 16, v128
	v_and_b32_e32 v221, 0xffff0000, v128
	v_lshlrev_b32_e32 v222, 16, v129
	v_and_b32_e32 v223, 0xffff0000, v129
	v_lshlrev_b32_e32 v224, 16, v130
	v_and_b32_e32 v225, 0xffff0000, v130
	v_lshlrev_b32_e32 v226, 16, v131
	v_and_b32_e32 v227, 0xffff0000, v131
	v_pk_mul_f32 v[220:221], v[190:191], v[220:221] op_sel_hi:[0,1]
	v_pk_mul_f32 v[222:223], v[190:191], v[222:223] op_sel_hi:[0,1]
	v_pk_mul_f32 v[224:225], v[190:191], v[224:225] op_sel_hi:[0,1]
	v_pk_mul_f32 v[226:227], v[190:191], v[226:227] op_sel_hi:[0,1]
	v_pk_fma_f32 v[124:125], v[228:229], v[220:221], v[124:125]
	v_pk_fma_f32 v[126:127], v[230:231], v[222:223], v[126:127]
	v_pk_fma_f32 v[120:121], v[232:233], v[224:225], v[120:121]
	v_pk_fma_f32 v[122:123], v[234:235], v[226:227], v[122:123]
	v_mul_f32_e32 v201, v124, v124
	v_fmac_f32_e32 v201, v125, v125
	v_fmac_f32_e32 v201, v126, v126
	v_fmac_f32_e32 v201, v127, v127
	v_fmac_f32_e32 v201, v120, v120
	v_fmac_f32_e32 v201, v121, v121
	v_fmac_f32_e32 v201, v122, v122
	v_fmac_f32_e32 v201, v123, v123
	v_cvt_pk_bf16_f32 v124, v124, v125
	v_cvt_pk_bf16_f32 v125, v126, v127
	v_cvt_pk_bf16_f32 v126, v120, v121
	v_cvt_pk_bf16_f32 v127, v122, v123
	global_store_dwordx4 v168, v[124:127], s[60:61]
	v_lshlrev_b32_e32 v220, 16, v132
	v_and_b32_e32 v221, 0xffff0000, v132
	v_lshlrev_b32_e32 v222, 16, v133
	v_and_b32_e32 v223, 0xffff0000, v133
	v_lshlrev_b32_e32 v224, 16, v134
	v_and_b32_e32 v225, 0xffff0000, v134
	v_lshlrev_b32_e32 v226, 16, v135
	v_and_b32_e32 v227, 0xffff0000, v135
	v_pk_mul_f32 v[220:221], v[190:191], v[220:221] op_sel_hi:[0,1]
	v_pk_mul_f32 v[222:223], v[190:191], v[222:223] op_sel_hi:[0,1]
	v_pk_mul_f32 v[224:225], v[190:191], v[224:225] op_sel_hi:[0,1]
	v_pk_mul_f32 v[226:227], v[190:191], v[226:227] op_sel_hi:[0,1]
	v_pk_fma_f32 v[116:117], v[180:181], v[220:221], v[116:117]
	v_pk_fma_f32 v[118:119], v[182:183], v[222:223], v[118:119]
	v_pk_fma_f32 v[112:113], v[184:185], v[224:225], v[112:113]
	v_pk_fma_f32 v[114:115], v[186:187], v[226:227], v[114:115]
	v_fmac_f32_e32 v201, v116, v116
	v_fmac_f32_e32 v201, v117, v117
	v_fmac_f32_e32 v201, v118, v118
	v_fmac_f32_e32 v201, v119, v119
	v_fmac_f32_e32 v201, v112, v112
	v_fmac_f32_e32 v201, v113, v113
	v_fmac_f32_e32 v201, v114, v114
	v_fmac_f32_e32 v201, v115, v115
	v_cvt_pk_bf16_f32 v116, v116, v117
	v_cvt_pk_bf16_f32 v117, v118, v119
	v_cvt_pk_bf16_f32 v118, v112, v113
	v_cvt_pk_bf16_f32 v119, v114, v115
	global_store_dwordx4 v168, v[116:119], s[60:61] offset:256
	v_add_f32_dpp v201, v201, v201 quad_perm:[1,0,3,2] row_mask:0xf bank_mask:0xf
	s_nop 1
	v_add_f32_dpp v201, v201, v201 quad_perm:[2,3,0,1] row_mask:0xf bank_mask:0xf
	s_mov_b64 exec, s[10:11]
	global_atomic_add_f32 v176, v201, s[14:15]
	s_mov_b64 exec, -1
	global_load_dword v190, v176, s[12:13] offset:512
	global_load_dwordx4 v[128:131], v172, s[60:61]
	global_load_dwordx4 v[132:135], v172, s[60:61] offset:256
	s_waitcnt vmcnt(12)
	v_lshlrev_b32_e32 v220, 16, v136
	v_and_b32_e32 v221, 0xffff0000, v136
	v_lshlrev_b32_e32 v222, 16, v137
	v_and_b32_e32 v223, 0xffff0000, v137
	v_lshlrev_b32_e32 v224, 16, v138
	v_and_b32_e32 v225, 0xffff0000, v138
	v_lshlrev_b32_e32 v226, 16, v139
	v_and_b32_e32 v227, 0xffff0000, v139
	v_pk_mul_f32 v[220:221], v[192:193], v[220:221] op_sel_hi:[0,1]
	v_pk_mul_f32 v[222:223], v[192:193], v[222:223] op_sel_hi:[0,1]
	v_pk_mul_f32 v[224:225], v[192:193], v[224:225] op_sel_hi:[0,1]
	v_pk_mul_f32 v[226:227], v[192:193], v[226:227] op_sel_hi:[0,1]
	v_pk_fma_f32 v[108:109], v[228:229], v[220:221], v[108:109]
	v_pk_fma_f32 v[110:111], v[230:231], v[222:223], v[110:111]
	v_pk_fma_f32 v[104:105], v[232:233], v[224:225], v[104:105]
	v_pk_fma_f32 v[106:107], v[234:235], v[226:227], v[106:107]
	v_mul_f32_e32 v202, v108, v108
	v_fmac_f32_e32 v202, v109, v109
	v_fmac_f32_e32 v202, v110, v110
	v_fmac_f32_e32 v202, v111, v111
	v_fmac_f32_e32 v202, v104, v104
	v_fmac_f32_e32 v202, v105, v105
	v_fmac_f32_e32 v202, v106, v106
	v_fmac_f32_e32 v202, v107, v107
	v_cvt_pk_bf16_f32 v108, v108, v109
	v_cvt_pk_bf16_f32 v109, v110, v111
	v_cvt_pk_bf16_f32 v110, v104, v105
	v_cvt_pk_bf16_f32 v111, v106, v107
	global_store_dwordx4 v169, v[108:111], s[60:61]
	v_lshlrev_b32_e32 v220, 16, v140
	v_and_b32_e32 v221, 0xffff0000, v140
	v_lshlrev_b32_e32 v222, 16, v141
	v_and_b32_e32 v223, 0xffff0000, v141
	v_lshlrev_b32_e32 v224, 16, v142
	v_and_b32_e32 v225, 0xffff0000, v142
	v_lshlrev_b32_e32 v226, 16, v143
	v_and_b32_e32 v227, 0xffff0000, v143
	v_pk_mul_f32 v[220:221], v[192:193], v[220:221] op_sel_hi:[0,1]
	v_pk_mul_f32 v[222:223], v[192:193], v[222:223] op_sel_hi:[0,1]
	v_pk_mul_f32 v[224:225], v[192:193], v[224:225] op_sel_hi:[0,1]
	v_pk_mul_f32 v[226:227], v[192:193], v[226:227] op_sel_hi:[0,1]
	v_pk_fma_f32 v[100:101], v[180:181], v[220:221], v[100:101]
	v_pk_fma_f32 v[102:103], v[182:183], v[222:223], v[102:103]
	v_pk_fma_f32 v[96:97], v[184:185], v[224:225], v[96:97]
	v_pk_fma_f32 v[98:99], v[186:187], v[226:227], v[98:99]
	v_fmac_f32_e32 v202, v100, v100
	v_fmac_f32_e32 v202, v101, v101
	v_fmac_f32_e32 v202, v102, v102
	v_fmac_f32_e32 v202, v103, v103
	v_fmac_f32_e32 v202, v96, v96
	v_fmac_f32_e32 v202, v97, v97
	v_fmac_f32_e32 v202, v98, v98
	v_fmac_f32_e32 v202, v99, v99
	v_cvt_pk_bf16_f32 v100, v100, v101
	v_cvt_pk_bf16_f32 v101, v102, v103
	v_cvt_pk_bf16_f32 v102, v96, v97
	v_cvt_pk_bf16_f32 v103, v98, v99
	global_store_dwordx4 v169, v[100:103], s[60:61] offset:256
	v_add_f32_dpp v202, v202, v202 quad_perm:[1,0,3,2] row_mask:0xf bank_mask:0xf
	s_nop 1
	v_add_f32_dpp v202, v202, v202 quad_perm:[2,3,0,1] row_mask:0xf bank_mask:0xf
	s_mov_b64 exec, s[10:11]
	global_atomic_add_f32 v176, v202, s[14:15] offset:64
	s_mov_b64 exec, -1
	global_load_dword v192, v176, s[12:13] offset:576
	global_load_dwordx4 v[136:139], v173, s[60:61]
	global_load_dwordx4 v[140:143], v173, s[60:61] offset:256
	s_waitcnt vmcnt(15)
	v_lshlrev_b32_e32 v220, 16, v144
	v_and_b32_e32 v221, 0xffff0000, v144
	v_lshlrev_b32_e32 v222, 16, v145
	v_and_b32_e32 v223, 0xffff0000, v145
	v_lshlrev_b32_e32 v224, 16, v146
	v_and_b32_e32 v225, 0xffff0000, v146
	v_lshlrev_b32_e32 v226, 16, v147
	v_and_b32_e32 v227, 0xffff0000, v147
	v_pk_mul_f32 v[220:221], v[194:195], v[220:221] op_sel_hi:[0,1]
	v_pk_mul_f32 v[222:223], v[194:195], v[222:223] op_sel_hi:[0,1]
	v_pk_mul_f32 v[224:225], v[194:195], v[224:225] op_sel_hi:[0,1]
	v_pk_mul_f32 v[226:227], v[194:195], v[226:227] op_sel_hi:[0,1]
	v_pk_fma_f32 v[92:93], v[228:229], v[220:221], v[92:93]
	v_pk_fma_f32 v[94:95], v[230:231], v[222:223], v[94:95]
	v_pk_fma_f32 v[88:89], v[232:233], v[224:225], v[88:89]
	v_pk_fma_f32 v[90:91], v[234:235], v[226:227], v[90:91]
	v_mul_f32_e32 v201, v92, v92
	v_fmac_f32_e32 v201, v93, v93
	v_fmac_f32_e32 v201, v94, v94
	v_fmac_f32_e32 v201, v95, v95
	v_fmac_f32_e32 v201, v88, v88
	v_fmac_f32_e32 v201, v89, v89
	v_fmac_f32_e32 v201, v90, v90
	v_fmac_f32_e32 v201, v91, v91
	v_cvt_pk_bf16_f32 v92, v92, v93
	v_cvt_pk_bf16_f32 v93, v94, v95
	v_cvt_pk_bf16_f32 v94, v88, v89
	v_cvt_pk_bf16_f32 v95, v90, v91
	global_store_dwordx4 v170, v[92:95], s[60:61]
	v_lshlrev_b32_e32 v220, 16, v148
	v_and_b32_e32 v221, 0xffff0000, v148
	v_lshlrev_b32_e32 v222, 16, v149
	v_and_b32_e32 v223, 0xffff0000, v149
	v_lshlrev_b32_e32 v224, 16, v150
	v_and_b32_e32 v225, 0xffff0000, v150
	v_lshlrev_b32_e32 v226, 16, v151
	v_and_b32_e32 v227, 0xffff0000, v151
	v_pk_mul_f32 v[220:221], v[194:195], v[220:221] op_sel_hi:[0,1]
	v_pk_mul_f32 v[222:223], v[194:195], v[222:223] op_sel_hi:[0,1]
	v_pk_mul_f32 v[224:225], v[194:195], v[224:225] op_sel_hi:[0,1]
	v_pk_mul_f32 v[226:227], v[194:195], v[226:227] op_sel_hi:[0,1]
	v_pk_fma_f32 v[84:85], v[180:181], v[220:221], v[84:85]
	v_pk_fma_f32 v[86:87], v[182:183], v[222:223], v[86:87]
	v_pk_fma_f32 v[80:81], v[184:185], v[224:225], v[80:81]
	v_pk_fma_f32 v[82:83], v[186:187], v[226:227], v[82:83]
	v_fmac_f32_e32 v201, v84, v84
	v_fmac_f32_e32 v201, v85, v85
	v_fmac_f32_e32 v201, v86, v86
	v_fmac_f32_e32 v201, v87, v87
	v_fmac_f32_e32 v201, v80, v80
	v_fmac_f32_e32 v201, v81, v81
	v_fmac_f32_e32 v201, v82, v82
	v_fmac_f32_e32 v201, v83, v83
	v_cvt_pk_bf16_f32 v84, v84, v85
	v_cvt_pk_bf16_f32 v85, v86, v87
	v_cvt_pk_bf16_f32 v86, v80, v81
	v_cvt_pk_bf16_f32 v87, v82, v83
	global_store_dwordx4 v170, v[84:87], s[60:61] offset:256
	v_add_f32_dpp v201, v201, v201 quad_perm:[1,0,3,2] row_mask:0xf bank_mask:0xf
	s_nop 1
	v_add_f32_dpp v201, v201, v201 quad_perm:[2,3,0,1] row_mask:0xf bank_mask:0xf
	s_mov_b64 exec, s[10:11]
	global_atomic_add_f32 v176, v201, s[14:15] offset:128
	s_mov_b64 exec, -1
	global_load_dword v194, v176, s[12:13] offset:640
	global_load_dwordx4 v[144:147], v174, s[60:61]
	global_load_dwordx4 v[148:151], v174, s[60:61] offset:256
	s_waitcnt vmcnt(18)
	v_lshlrev_b32_e32 v220, 16, v204
	v_and_b32_e32 v221, 0xffff0000, v204
	v_lshlrev_b32_e32 v222, 16, v205
	v_and_b32_e32 v223, 0xffff0000, v205
	v_lshlrev_b32_e32 v224, 16, v206
	v_and_b32_e32 v225, 0xffff0000, v206
	v_lshlrev_b32_e32 v226, 16, v207
	v_and_b32_e32 v227, 0xffff0000, v207
	v_pk_mul_f32 v[220:221], v[238:239], v[220:221] op_sel_hi:[0,1]
	v_pk_mul_f32 v[222:223], v[238:239], v[222:223] op_sel_hi:[0,1]
	v_pk_mul_f32 v[224:225], v[238:239], v[224:225] op_sel_hi:[0,1]
	v_pk_mul_f32 v[226:227], v[238:239], v[226:227] op_sel_hi:[0,1]
	v_pk_fma_f32 v[76:77], v[228:229], v[220:221], v[76:77]
	v_pk_fma_f32 v[78:79], v[230:231], v[222:223], v[78:79]
	v_pk_fma_f32 v[72:73], v[232:233], v[224:225], v[72:73]
	v_pk_fma_f32 v[74:75], v[234:235], v[226:227], v[74:75]
	v_mul_f32_e32 v202, v76, v76
	v_fmac_f32_e32 v202, v77, v77
	v_fmac_f32_e32 v202, v78, v78
	v_fmac_f32_e32 v202, v79, v79
	v_fmac_f32_e32 v202, v72, v72
	v_fmac_f32_e32 v202, v73, v73
	v_fmac_f32_e32 v202, v74, v74
	v_fmac_f32_e32 v202, v75, v75
	v_cvt_pk_bf16_f32 v76, v76, v77
	v_cvt_pk_bf16_f32 v77, v78, v79
	v_cvt_pk_bf16_f32 v78, v72, v73
	v_cvt_pk_bf16_f32 v79, v74, v75
	global_store_dwordx4 v171, v[76:79], s[60:61]
	v_lshlrev_b32_e32 v220, 16, v216
	v_and_b32_e32 v221, 0xffff0000, v216
	v_lshlrev_b32_e32 v222, 16, v217
	v_and_b32_e32 v223, 0xffff0000, v217
	v_lshlrev_b32_e32 v224, 16, v218
	v_and_b32_e32 v225, 0xffff0000, v218
	v_lshlrev_b32_e32 v226, 16, v219
	v_and_b32_e32 v227, 0xffff0000, v219
	v_pk_mul_f32 v[220:221], v[238:239], v[220:221] op_sel_hi:[0,1]
	v_pk_mul_f32 v[222:223], v[238:239], v[222:223] op_sel_hi:[0,1]
	v_pk_mul_f32 v[224:225], v[238:239], v[224:225] op_sel_hi:[0,1]
	v_pk_mul_f32 v[226:227], v[238:239], v[226:227] op_sel_hi:[0,1]
	v_pk_fma_f32 v[68:69], v[180:181], v[220:221], v[68:69]
	v_pk_fma_f32 v[70:71], v[182:183], v[222:223], v[70:71]
	v_pk_fma_f32 v[64:65], v[184:185], v[224:225], v[64:65]
	v_pk_fma_f32 v[66:67], v[186:187], v[226:227], v[66:67]
	v_fmac_f32_e32 v202, v68, v68
	v_fmac_f32_e32 v202, v69, v69
	v_fmac_f32_e32 v202, v70, v70
	v_fmac_f32_e32 v202, v71, v71
	v_fmac_f32_e32 v202, v64, v64
	v_fmac_f32_e32 v202, v65, v65
	v_fmac_f32_e32 v202, v66, v66
	v_fmac_f32_e32 v202, v67, v67
	v_cvt_pk_bf16_f32 v68, v68, v69
	v_cvt_pk_bf16_f32 v69, v70, v71
	v_cvt_pk_bf16_f32 v70, v64, v65
	v_cvt_pk_bf16_f32 v71, v66, v67
	global_store_dwordx4 v171, v[68:71], s[60:61] offset:256
	v_add_f32_dpp v202, v202, v202 quad_perm:[1,0,3,2] row_mask:0xf bank_mask:0xf
	s_nop 1
	v_add_f32_dpp v202, v202, v202 quad_perm:[2,3,0,1] row_mask:0xf bank_mask:0xf
	s_mov_b64 exec, s[10:11]
	global_atomic_add_f32 v176, v202, s[14:15] offset:192
	s_mov_b64 exec, -1
	global_load_dword v238, v176, s[12:13] offset:704
	global_load_dwordx4 v[204:207], v175, s[60:61]
	global_load_dwordx4 v[216:219], v175, s[60:61] offset:256
	s_waitcnt vmcnt(18)
	v_lshlrev_b32_e32 v220, 16, v128
	v_and_b32_e32 v221, 0xffff0000, v128
	v_lshlrev_b32_e32 v222, 16, v129
	v_and_b32_e32 v223, 0xffff0000, v129
	v_lshlrev_b32_e32 v224, 16, v130
	v_and_b32_e32 v225, 0xffff0000, v130
	v_lshlrev_b32_e32 v226, 16, v131
	v_and_b32_e32 v227, 0xffff0000, v131
	v_pk_mul_f32 v[220:221], v[190:191], v[220:221] op_sel_hi:[0,1]
	v_pk_mul_f32 v[222:223], v[190:191], v[222:223] op_sel_hi:[0,1]
	v_pk_mul_f32 v[224:225], v[190:191], v[224:225] op_sel_hi:[0,1]
	v_pk_mul_f32 v[226:227], v[190:191], v[226:227] op_sel_hi:[0,1]
	v_pk_fma_f32 v[60:61], v[228:229], v[220:221], v[60:61]
	v_pk_fma_f32 v[62:63], v[230:231], v[222:223], v[62:63]
	v_pk_fma_f32 v[56:57], v[232:233], v[224:225], v[56:57]
	v_pk_fma_f32 v[58:59], v[234:235], v[226:227], v[58:59]
	v_mul_f32_e32 v201, v60, v60
	v_fmac_f32_e32 v201, v61, v61
	v_fmac_f32_e32 v201, v62, v62
	v_fmac_f32_e32 v201, v63, v63
	v_fmac_f32_e32 v201, v56, v56
	v_fmac_f32_e32 v201, v57, v57
	v_fmac_f32_e32 v201, v58, v58
	v_fmac_f32_e32 v201, v59, v59
	v_cvt_pk_bf16_f32 v60, v60, v61
	v_cvt_pk_bf16_f32 v61, v62, v63
	v_cvt_pk_bf16_f32 v62, v56, v57
	v_cvt_pk_bf16_f32 v63, v58, v59
	global_store_dwordx4 v172, v[60:63], s[60:61]
	v_lshlrev_b32_e32 v220, 16, v132
	v_and_b32_e32 v221, 0xffff0000, v132
	v_lshlrev_b32_e32 v222, 16, v133
	v_and_b32_e32 v223, 0xffff0000, v133
	v_lshlrev_b32_e32 v224, 16, v134
	v_and_b32_e32 v225, 0xffff0000, v134
	v_lshlrev_b32_e32 v226, 16, v135
	v_and_b32_e32 v227, 0xffff0000, v135
	v_pk_mul_f32 v[220:221], v[190:191], v[220:221] op_sel_hi:[0,1]
	v_pk_mul_f32 v[222:223], v[190:191], v[222:223] op_sel_hi:[0,1]
	v_pk_mul_f32 v[224:225], v[190:191], v[224:225] op_sel_hi:[0,1]
	v_pk_mul_f32 v[226:227], v[190:191], v[226:227] op_sel_hi:[0,1]
	v_pk_fma_f32 v[52:53], v[180:181], v[220:221], v[52:53]
	v_pk_fma_f32 v[54:55], v[182:183], v[222:223], v[54:55]
	v_pk_fma_f32 v[48:49], v[184:185], v[224:225], v[48:49]
	v_pk_fma_f32 v[50:51], v[186:187], v[226:227], v[50:51]
	v_fmac_f32_e32 v201, v52, v52
	v_fmac_f32_e32 v201, v53, v53
	v_fmac_f32_e32 v201, v54, v54
	v_fmac_f32_e32 v201, v55, v55
	v_fmac_f32_e32 v201, v48, v48
	v_fmac_f32_e32 v201, v49, v49
	v_fmac_f32_e32 v201, v50, v50
	v_fmac_f32_e32 v201, v51, v51
	v_cvt_pk_bf16_f32 v52, v52, v53
	v_cvt_pk_bf16_f32 v53, v54, v55
	v_cvt_pk_bf16_f32 v54, v48, v49
	v_cvt_pk_bf16_f32 v55, v50, v51
	global_store_dwordx4 v172, v[52:55], s[60:61] offset:256
	v_add_f32_dpp v201, v201, v201 quad_perm:[1,0,3,2] row_mask:0xf bank_mask:0xf
	s_nop 1
	v_add_f32_dpp v201, v201, v201 quad_perm:[2,3,0,1] row_mask:0xf bank_mask:0xf
	s_mov_b64 exec, s[10:11]
	global_atomic_add_f32 v176, v201, s[14:15] offset:512
	s_mov_b64 exec, -1
	s_waitcnt vmcnt(15)
	v_lshlrev_b32_e32 v220, 16, v136
	v_and_b32_e32 v221, 0xffff0000, v136
	v_lshlrev_b32_e32 v222, 16, v137
	v_and_b32_e32 v223, 0xffff0000, v137
	v_lshlrev_b32_e32 v224, 16, v138
	v_and_b32_e32 v225, 0xffff0000, v138
	v_lshlrev_b32_e32 v226, 16, v139
	v_and_b32_e32 v227, 0xffff0000, v139
	v_pk_mul_f32 v[220:221], v[192:193], v[220:221] op_sel_hi:[0,1]
	v_pk_mul_f32 v[222:223], v[192:193], v[222:223] op_sel_hi:[0,1]
	v_pk_mul_f32 v[224:225], v[192:193], v[224:225] op_sel_hi:[0,1]
	v_pk_mul_f32 v[226:227], v[192:193], v[226:227] op_sel_hi:[0,1]
	v_pk_fma_f32 v[44:45], v[228:229], v[220:221], v[44:45]
	v_pk_fma_f32 v[46:47], v[230:231], v[222:223], v[46:47]
	v_pk_fma_f32 v[40:41], v[232:233], v[224:225], v[40:41]
	v_pk_fma_f32 v[42:43], v[234:235], v[226:227], v[42:43]
	v_mul_f32_e32 v202, v44, v44
	v_fmac_f32_e32 v202, v45, v45
	v_fmac_f32_e32 v202, v46, v46
	v_fmac_f32_e32 v202, v47, v47
	v_fmac_f32_e32 v202, v40, v40
	v_fmac_f32_e32 v202, v41, v41
	v_fmac_f32_e32 v202, v42, v42
	v_fmac_f32_e32 v202, v43, v43
	v_cvt_pk_bf16_f32 v44, v44, v45
	v_cvt_pk_bf16_f32 v45, v46, v47
	v_cvt_pk_bf16_f32 v46, v40, v41
	v_cvt_pk_bf16_f32 v47, v42, v43
	global_store_dwordx4 v173, v[44:47], s[60:61]
	v_lshlrev_b32_e32 v220, 16, v140
	v_and_b32_e32 v221, 0xffff0000, v140
	v_lshlrev_b32_e32 v222, 16, v141
	v_and_b32_e32 v223, 0xffff0000, v141
	v_lshlrev_b32_e32 v224, 16, v142
	v_and_b32_e32 v225, 0xffff0000, v142
	v_lshlrev_b32_e32 v226, 16, v143
	v_and_b32_e32 v227, 0xffff0000, v143
	v_pk_mul_f32 v[220:221], v[192:193], v[220:221] op_sel_hi:[0,1]
	v_pk_mul_f32 v[222:223], v[192:193], v[222:223] op_sel_hi:[0,1]
	v_pk_mul_f32 v[224:225], v[192:193], v[224:225] op_sel_hi:[0,1]
	v_pk_mul_f32 v[226:227], v[192:193], v[226:227] op_sel_hi:[0,1]
	v_pk_fma_f32 v[36:37], v[180:181], v[220:221], v[36:37]
	v_pk_fma_f32 v[38:39], v[182:183], v[222:223], v[38:39]
	v_pk_fma_f32 v[32:33], v[184:185], v[224:225], v[32:33]
	v_pk_fma_f32 v[34:35], v[186:187], v[226:227], v[34:35]
	v_fmac_f32_e32 v202, v36, v36
	v_fmac_f32_e32 v202, v37, v37
	v_fmac_f32_e32 v202, v38, v38
	v_fmac_f32_e32 v202, v39, v39
	v_fmac_f32_e32 v202, v32, v32
	v_fmac_f32_e32 v202, v33, v33
	v_fmac_f32_e32 v202, v34, v34
	v_fmac_f32_e32 v202, v35, v35
	v_cvt_pk_bf16_f32 v36, v36, v37
	v_cvt_pk_bf16_f32 v37, v38, v39
	v_cvt_pk_bf16_f32 v38, v32, v33
	v_cvt_pk_bf16_f32 v39, v34, v35
	global_store_dwordx4 v173, v[36:39], s[60:61] offset:256
	v_add_f32_dpp v202, v202, v202 quad_perm:[1,0,3,2] row_mask:0xf bank_mask:0xf
	s_nop 1
	v_add_f32_dpp v202, v202, v202 quad_perm:[2,3,0,1] row_mask:0xf bank_mask:0xf
	s_mov_b64 exec, s[10:11]
	global_atomic_add_f32 v176, v202, s[14:15] offset:576
	s_mov_b64 exec, -1
	s_waitcnt vmcnt(12)
	v_lshlrev_b32_e32 v220, 16, v144
	v_and_b32_e32 v221, 0xffff0000, v144
	v_lshlrev_b32_e32 v222, 16, v145
	v_and_b32_e32 v223, 0xffff0000, v145
	v_lshlrev_b32_e32 v224, 16, v146
	v_and_b32_e32 v225, 0xffff0000, v146
	v_lshlrev_b32_e32 v226, 16, v147
	v_and_b32_e32 v227, 0xffff0000, v147
	v_pk_mul_f32 v[220:221], v[194:195], v[220:221] op_sel_hi:[0,1]
	v_pk_mul_f32 v[222:223], v[194:195], v[222:223] op_sel_hi:[0,1]
	v_pk_mul_f32 v[224:225], v[194:195], v[224:225] op_sel_hi:[0,1]
	v_pk_mul_f32 v[226:227], v[194:195], v[226:227] op_sel_hi:[0,1]
	v_pk_fma_f32 v[28:29], v[228:229], v[220:221], v[28:29]
	v_pk_fma_f32 v[30:31], v[230:231], v[222:223], v[30:31]
	v_pk_fma_f32 v[24:25], v[232:233], v[224:225], v[24:25]
	v_pk_fma_f32 v[26:27], v[234:235], v[226:227], v[26:27]
	v_mul_f32_e32 v201, v28, v28
	v_fmac_f32_e32 v201, v29, v29
	v_fmac_f32_e32 v201, v30, v30
	v_fmac_f32_e32 v201, v31, v31
	v_fmac_f32_e32 v201, v24, v24
	v_fmac_f32_e32 v201, v25, v25
	v_fmac_f32_e32 v201, v26, v26
	v_fmac_f32_e32 v201, v27, v27
	v_cvt_pk_bf16_f32 v28, v28, v29
	v_cvt_pk_bf16_f32 v29, v30, v31
	v_cvt_pk_bf16_f32 v30, v24, v25
	v_cvt_pk_bf16_f32 v31, v26, v27
	global_store_dwordx4 v174, v[28:31], s[60:61]
	v_lshlrev_b32_e32 v220, 16, v148
	v_and_b32_e32 v221, 0xffff0000, v148
	v_lshlrev_b32_e32 v222, 16, v149
	v_and_b32_e32 v223, 0xffff0000, v149
	v_lshlrev_b32_e32 v224, 16, v150
	v_and_b32_e32 v225, 0xffff0000, v150
	v_lshlrev_b32_e32 v226, 16, v151
	v_and_b32_e32 v227, 0xffff0000, v151
	v_pk_mul_f32 v[220:221], v[194:195], v[220:221] op_sel_hi:[0,1]
	v_pk_mul_f32 v[222:223], v[194:195], v[222:223] op_sel_hi:[0,1]
	v_pk_mul_f32 v[224:225], v[194:195], v[224:225] op_sel_hi:[0,1]
	v_pk_mul_f32 v[226:227], v[194:195], v[226:227] op_sel_hi:[0,1]
	v_pk_fma_f32 v[20:21], v[180:181], v[220:221], v[20:21]
	v_pk_fma_f32 v[22:23], v[182:183], v[222:223], v[22:23]
	v_pk_fma_f32 v[16:17], v[184:185], v[224:225], v[16:17]
	v_pk_fma_f32 v[18:19], v[186:187], v[226:227], v[18:19]
	v_fmac_f32_e32 v201, v20, v20
	v_fmac_f32_e32 v201, v21, v21
	v_fmac_f32_e32 v201, v22, v22
	v_fmac_f32_e32 v201, v23, v23
	v_fmac_f32_e32 v201, v16, v16
	v_fmac_f32_e32 v201, v17, v17
	v_fmac_f32_e32 v201, v18, v18
	v_fmac_f32_e32 v201, v19, v19
	v_cvt_pk_bf16_f32 v20, v20, v21
	v_cvt_pk_bf16_f32 v21, v22, v23
	v_cvt_pk_bf16_f32 v22, v16, v17
	v_cvt_pk_bf16_f32 v23, v18, v19
	global_store_dwordx4 v174, v[20:23], s[60:61] offset:256
	v_add_f32_dpp v201, v201, v201 quad_perm:[1,0,3,2] row_mask:0xf bank_mask:0xf
	s_nop 1
	v_add_f32_dpp v201, v201, v201 quad_perm:[2,3,0,1] row_mask:0xf bank_mask:0xf
	s_mov_b64 exec, s[10:11]
	global_atomic_add_f32 v176, v201, s[14:15] offset:640
	s_mov_b64 exec, -1
	s_waitcnt vmcnt(9)
	v_lshlrev_b32_e32 v220, 16, v204
	v_and_b32_e32 v221, 0xffff0000, v204
	v_lshlrev_b32_e32 v222, 16, v205
	v_and_b32_e32 v223, 0xffff0000, v205
	v_lshlrev_b32_e32 v224, 16, v206
	v_and_b32_e32 v225, 0xffff0000, v206
	v_lshlrev_b32_e32 v226, 16, v207
	v_and_b32_e32 v227, 0xffff0000, v207
	v_pk_mul_f32 v[220:221], v[238:239], v[220:221] op_sel_hi:[0,1]
	v_pk_mul_f32 v[222:223], v[238:239], v[222:223] op_sel_hi:[0,1]
	v_pk_mul_f32 v[224:225], v[238:239], v[224:225] op_sel_hi:[0,1]
	v_pk_mul_f32 v[226:227], v[238:239], v[226:227] op_sel_hi:[0,1]
	v_pk_fma_f32 v[12:13], v[228:229], v[220:221], v[12:13]
	v_pk_fma_f32 v[14:15], v[230:231], v[222:223], v[14:15]
	v_pk_fma_f32 v[8:9], v[232:233], v[224:225], v[8:9]
	v_pk_fma_f32 v[10:11], v[234:235], v[226:227], v[10:11]
	v_mul_f32_e32 v202, v12, v12
	v_fmac_f32_e32 v202, v13, v13
	v_fmac_f32_e32 v202, v14, v14
	v_fmac_f32_e32 v202, v15, v15
	v_fmac_f32_e32 v202, v8, v8
	v_fmac_f32_e32 v202, v9, v9
	v_fmac_f32_e32 v202, v10, v10
	v_fmac_f32_e32 v202, v11, v11
	v_cvt_pk_bf16_f32 v12, v12, v13
	v_cvt_pk_bf16_f32 v13, v14, v15
	v_cvt_pk_bf16_f32 v14, v8, v9
	v_cvt_pk_bf16_f32 v15, v10, v11
	global_store_dwordx4 v175, v[12:15], s[60:61]
	v_lshlrev_b32_e32 v220, 16, v216
	v_and_b32_e32 v221, 0xffff0000, v216
	v_lshlrev_b32_e32 v222, 16, v217
	v_and_b32_e32 v223, 0xffff0000, v217
	v_lshlrev_b32_e32 v224, 16, v218
	v_and_b32_e32 v225, 0xffff0000, v218
	v_lshlrev_b32_e32 v226, 16, v219
	v_and_b32_e32 v227, 0xffff0000, v219
	v_pk_mul_f32 v[220:221], v[238:239], v[220:221] op_sel_hi:[0,1]
	v_pk_mul_f32 v[222:223], v[238:239], v[222:223] op_sel_hi:[0,1]
	v_pk_mul_f32 v[224:225], v[238:239], v[224:225] op_sel_hi:[0,1]
	v_pk_mul_f32 v[226:227], v[238:239], v[226:227] op_sel_hi:[0,1]
	v_pk_fma_f32 v[4:5], v[180:181], v[220:221], v[4:5]
	v_pk_fma_f32 v[6:7], v[182:183], v[222:223], v[6:7]
	v_pk_fma_f32 v[0:1], v[184:185], v[224:225], v[0:1]
	v_pk_fma_f32 v[2:3], v[186:187], v[226:227], v[2:3]
	v_fmac_f32_e32 v202, v4, v4
	v_fmac_f32_e32 v202, v5, v5
	v_fmac_f32_e32 v202, v6, v6
	v_fmac_f32_e32 v202, v7, v7
	v_fmac_f32_e32 v202, v0, v0
	v_fmac_f32_e32 v202, v1, v1
	v_fmac_f32_e32 v202, v2, v2
	v_fmac_f32_e32 v202, v3, v3
	v_cvt_pk_bf16_f32 v4, v4, v5
	v_cvt_pk_bf16_f32 v5, v6, v7
	v_cvt_pk_bf16_f32 v6, v0, v1
	v_cvt_pk_bf16_f32 v7, v2, v3
	global_store_dwordx4 v175, v[4:7], s[60:61] offset:256
	v_add_f32_dpp v202, v202, v202 quad_perm:[1,0,3,2] row_mask:0xf bank_mask:0xf
	s_nop 1
	v_add_f32_dpp v202, v202, v202 quad_perm:[2,3,0,1] row_mask:0xf bank_mask:0xf
	s_mov_b64 exec, s[10:11]
	global_atomic_add_f32 v176, v202, s[14:15] offset:704
	s_mov_b64 exec, -1
	s_and_b64 vcc, exec, s[6:7]
	s_mov_b64 s[6:7], -1
	s_cbranch_vccnz .LBB0_852
	s_andn2_b64 vcc, exec, s[26:27]
	s_cbranch_vccnz .LBB0_851
	s_barrier
	s_branch .LBB0_851
